# baseline (speedup 1.0000x reference)
; __device__ __forceinline__ unsigned cvt_pk_bf16(float lo, float hi) { unsigned r; asm volatile("v_cvt_pk_bf16_f32 %0, %1, %2" : "=v"(r) : "v"(lo), "v"(hi)); return r; }
;     __device__ __forceinline__ void operator()(const f32x4 (&acc)[2][2][4][2], const Unit& u, int wr, int wc, int fr, int fq) const {
;         const int row0 = u.pm * BM + wr * 64 + fr; const int t = u.pn >> 2; bf16_t* base = O + (size_t)t * split_stride;
;         if (t == 2) {
;             const int col0 = (u.pn & 3) * BM + wc * 32 + 8 * fq;
; #pragma unroll
;             for (int ai = 0; ai < 2; ++ai)
; #pragma unroll
;                 for (int m = 0; m < 4; ++m) { const int row = row0 + ai * HALF + m * 16; const float rs = __builtin_amdgcn_rsqf((float)ssq[row] * (1.0f / (1024.0f * 1048576.0f)) + RMS_EPS);
;                     bf16_t* rowp = base + (size_t)row * 1024 + col0;
; #pragma unroll
;                     for (int bj = 0; bj < 2; ++bj) { const f32x4 v0 = acc[ai][bj][m][0] * rs, v1 = acc[ai][bj][m][1] * rs;
;                         u32x4 w; w.x = cvt_pk_bf16(v0[0], v0[1]); w.y = cvt_pk_bf16(v0[2], v0[3]); w.z = cvt_pk_bf16(v1[0], v1[1]); w.w = cvt_pk_bf16(v1[2], v1[3]);
;                         *(u32x4*)(rowp + bj * HALF) = w; }
;                     }
.LBB0_141:
	v_readlane_b32 s24, v255, 21
	v_readlane_b32 s25, v255, 22
	s_lshl_b32 s15, s47, 8
	s_and_b32 s15, s15, 0x300
	v_lshl_add_u64 v[150:151], v[148:149], 3, s[24:25]
	global_load_dwordx2 v[190:191], v[150:151], off
	global_load_dwordx2 v[192:193], v[150:151], off offset:128
	global_load_dwordx2 v[194:195], v[150:151], off offset:256
	global_load_dwordx2 v[196:197], v[150:151], off offset:384
	global_load_dwordx2 v[198:199], v[150:151], off offset:1024
	global_load_dwordx2 v[200:201], v[150:151], off offset:1152
	global_load_dwordx2 v[202:203], v[150:151], off offset:1280
	global_load_dwordx2 v[204:205], v[150:151], off offset:1408
	s_nop 0
	v_lshlrev_b64 v[148:149], 11, v[148:149]
	s_waitcnt vmcnt(0)
	v_ffbh_u32_e32 v0, v191
	v_min_u32_e32 v0, 32, v0
	v_lshlrev_b64 v[152:153], v0, v[190:191]
	v_min_u32_e32 v152, 1, v152
	v_or_b32_e32 v152, v153, v152
	v_cvt_f32_u32_e32 v152, v152
	v_sub_u32_e32 v0, 32, v0
	v_or_b32_e32 v153, s15, v185
	s_mov_b32 s15, 0x40000
	v_ldexp_f32 v0, v152, v0
	v_fmamk_f32 v0, v0, 0x30800000, v240
	v_rsq_f32_e32 v152, v0
	v_lshlrev_b32_e32 v0, 1, v153
	v_lshl_add_u64 v[154:155], s[22:23], 0, v[0:1]
	v_lshl_add_u64 v[148:149], v[154:155], 0, v[148:149]
	v_pk_mul_f32 v[128:129], v[128:129], v[152:153] op_sel_hi:[1,0]
	v_pk_mul_f32 v[126:127], v[126:127], v[152:153] op_sel_hi:[1,0]
	v_pk_mul_f32 v[124:125], v[124:125], v[152:153] op_sel_hi:[1,0]
	v_pk_mul_f32 v[122:123], v[122:123], v[152:153] op_sel_hi:[1,0]
	v_pk_mul_f32 v[120:121], v[120:121], v[152:153] op_sel_hi:[1,0]
	v_pk_mul_f32 v[118:119], v[118:119], v[152:153] op_sel_hi:[1,0]
	v_pk_mul_f32 v[156:157], v[116:117], v[152:153] op_sel_hi:[1,0]
	v_pk_mul_f32 v[152:153], v[114:115], v[152:153] op_sel_hi:[1,0]
	v_cvt_pk_bf16_f32 v114, v126, v127
	v_cvt_pk_bf16_f32 v115, v128, v129
	v_cvt_pk_bf16_f32 v116, v122, v123
	v_cvt_pk_bf16_f32 v117, v124, v125
	global_store_dwordx4 v[148:149], v[114:117], off
	s_mov_b64 s[22:23], 0x40000
	s_nop 0
	v_cvt_pk_bf16_f32 v114, v118, v119
	v_cvt_pk_bf16_f32 v115, v120, v121
	v_cvt_pk_bf16_f32 v116, v152, v153
	v_cvt_pk_bf16_f32 v117, v156, v157
	global_store_dwordx4 v[148:149], v[114:117], off offset:256
	v_ffbh_u32_e32 v0, v193
	v_min_u32_e32 v0, 32, v0
	v_lshlrev_b64 v[114:115], v0, v[192:193]
	v_min_u32_e32 v114, 1, v114
	v_or_b32_e32 v114, v115, v114
	v_cvt_f32_u32_e32 v114, v114
	v_sub_u32_e32 v0, 32, v0
	v_ldexp_f32 v0, v114, v0
	v_fmamk_f32 v0, v0, 0x30800000, v240
	v_rsq_f32_e32 v0, v0
	v_lshlrev_b64 v[114:115], 11, v[146:147]
	v_lshl_add_u64 v[114:115], v[154:155], 0, v[114:115]
	v_pk_mul_f32 v[112:113], v[112:113], v[0:1] op_sel_hi:[1,0]
	v_pk_mul_f32 v[110:111], v[110:111], v[0:1] op_sel_hi:[1,0]
	v_pk_mul_f32 v[108:109], v[108:109], v[0:1] op_sel_hi:[1,0]
	v_pk_mul_f32 v[106:107], v[106:107], v[0:1] op_sel_hi:[1,0]
	v_pk_mul_f32 v[116:117], v[100:101], v[0:1] op_sel_hi:[1,0]
	v_pk_mul_f32 v[118:119], v[98:99], v[0:1] op_sel_hi:[1,0]
	v_cvt_pk_bf16_f32 v98, v110, v111
	v_cvt_pk_bf16_f32 v99, v112, v113
	v_cvt_pk_bf16_f32 v100, v106, v107
	v_cvt_pk_bf16_f32 v101, v108, v109
	v_pk_mul_f32 v[104:105], v[104:105], v[0:1] op_sel_hi:[1,0]
	v_pk_mul_f32 v[102:103], v[102:103], v[0:1] op_sel_hi:[1,0]
	global_store_dwordx4 v[114:115], v[98:101], off
	s_nop 1
	v_cvt_pk_bf16_f32 v98, v102, v103
	v_cvt_pk_bf16_f32 v99, v104, v105
	v_cvt_pk_bf16_f32 v100, v118, v119
	v_cvt_pk_bf16_f32 v101, v116, v117
	global_store_dwordx4 v[114:115], v[98:101], off offset:256
	v_ffbh_u32_e32 v0, v195
	v_min_u32_e32 v0, 32, v0
	v_lshlrev_b64 v[98:99], v0, v[194:195]
	v_min_u32_e32 v98, 1, v98
	v_or_b32_e32 v98, v99, v98
	v_cvt_f32_u32_e32 v98, v98
	v_sub_u32_e32 v0, 32, v0
	v_ldexp_f32 v0, v98, v0
	v_fmamk_f32 v0, v0, 0x30800000, v240
	v_rsq_f32_e32 v0, v0
	v_lshlrev_b64 v[98:99], 11, v[144:145]
	v_lshl_add_u64 v[98:99], v[154:155], 0, v[98:99]
	v_pk_mul_f32 v[96:97], v[96:97], v[0:1] op_sel_hi:[1,0]
	v_pk_mul_f32 v[94:95], v[94:95], v[0:1] op_sel_hi:[1,0]
	v_pk_mul_f32 v[92:93], v[92:93], v[0:1] op_sel_hi:[1,0]
	v_pk_mul_f32 v[90:91], v[90:91], v[0:1] op_sel_hi:[1,0]
	v_pk_mul_f32 v[100:101], v[84:85], v[0:1] op_sel_hi:[1,0]
	v_pk_mul_f32 v[102:103], v[82:83], v[0:1] op_sel_hi:[1,0]
	v_cvt_pk_bf16_f32 v82, v94, v95
	v_cvt_pk_bf16_f32 v83, v96, v97
	v_cvt_pk_bf16_f32 v84, v90, v91
	v_cvt_pk_bf16_f32 v85, v92, v93
	v_pk_mul_f32 v[88:89], v[88:89], v[0:1] op_sel_hi:[1,0]
	v_pk_mul_f32 v[86:87], v[86:87], v[0:1] op_sel_hi:[1,0]
	global_store_dwordx4 v[98:99], v[82:85], off
	s_nop 1
	v_cvt_pk_bf16_f32 v82, v86, v87
	v_cvt_pk_bf16_f32 v83, v88, v89
	v_cvt_pk_bf16_f32 v84, v102, v103
	v_cvt_pk_bf16_f32 v85, v100, v101
	global_store_dwordx4 v[98:99], v[82:85], off offset:256
	v_ffbh_u32_e32 v0, v197
	v_min_u32_e32 v0, 32, v0
	v_lshlrev_b64 v[82:83], v0, v[196:197]
	v_min_u32_e32 v82, 1, v82
	v_or_b32_e32 v82, v83, v82
	v_cvt_f32_u32_e32 v82, v82
	v_sub_u32_e32 v0, 32, v0
	v_ldexp_f32 v0, v82, v0
	v_fmamk_f32 v0, v0, 0x30800000, v240
	v_rsq_f32_e32 v0, v0
	v_lshlrev_b64 v[82:83], 11, v[142:143]
	v_lshl_add_u64 v[82:83], v[154:155], 0, v[82:83]
	v_pk_mul_f32 v[80:81], v[80:81], v[0:1] op_sel_hi:[1,0]
	v_pk_mul_f32 v[78:79], v[78:79], v[0:1] op_sel_hi:[1,0]
	v_pk_mul_f32 v[76:77], v[76:77], v[0:1] op_sel_hi:[1,0]
	v_pk_mul_f32 v[74:75], v[74:75], v[0:1] op_sel_hi:[1,0]
	v_pk_mul_f32 v[84:85], v[68:69], v[0:1] op_sel_hi:[1,0]
	v_pk_mul_f32 v[86:87], v[66:67], v[0:1] op_sel_hi:[1,0]
	v_cvt_pk_bf16_f32 v66, v78, v79
	v_cvt_pk_bf16_f32 v67, v80, v81
	v_cvt_pk_bf16_f32 v68, v74, v75
	v_cvt_pk_bf16_f32 v69, v76, v77
	v_pk_mul_f32 v[72:73], v[72:73], v[0:1] op_sel_hi:[1,0]
; __device__ __forceinline__ unsigned cvt_pk_bf16(float lo, float hi) { unsigned r; asm volatile("v_cvt_pk_bf16_f32 %0, %1, %2" : "=v"(r) : "v"(lo), "v"(hi)); return r; }
;     __device__ __forceinline__ void operator()(const f32x4 (&acc)[2][2][4][2], const Unit& u, int wr, int wc, int fr, int fq) const {
;     ...
;             for (int ai = 0; ai < 2; ++ai)
; #pragma unroll
;                 for (int m = 0; m < 4; ++m) { const int row = row0 + ai * HALF + m * 16; const float rs = __builtin_amdgcn_rsqf((float)ssq[row] * (1.0f / (1024.0f * 1048576.0f)) + RMS_EPS);
;                     bf16_t* rowp = base + (size_t)row * 1024 + col0;
; #pragma unroll
;                     for (int bj = 0; bj < 2; ++bj) { const f32x4 v0 = acc[ai][bj][m][0] * rs, v1 = acc[ai][bj][m][1] * rs;
;                         u32x4 w; w.x = cvt_pk_bf16(v0[0], v0[1]); w.y = cvt_pk_bf16(v0[2], v0[3]); w.z = cvt_pk_bf16(v1[0], v1[1]); w.w = cvt_pk_bf16(v1[2], v1[3]);
;                         *(u32x4*)(rowp + bj * HALF) = w; }
;                     }
	v_pk_mul_f32 v[70:71], v[70:71], v[0:1] op_sel_hi:[1,0]
	global_store_dwordx4 v[82:83], v[66:69], off
	s_nop 1
	v_cvt_pk_bf16_f32 v66, v70, v71
	v_cvt_pk_bf16_f32 v67, v72, v73
	v_cvt_pk_bf16_f32 v68, v86, v87
	v_cvt_pk_bf16_f32 v69, v84, v85
	global_store_dwordx4 v[82:83], v[66:69], off offset:256
	v_ffbh_u32_e32 v0, v199
	v_min_u32_e32 v0, 32, v0
	v_lshlrev_b64 v[66:67], v0, v[198:199]
	v_min_u32_e32 v66, 1, v66
	v_or_b32_e32 v66, v67, v66
	v_cvt_f32_u32_e32 v68, v66
	v_sub_u32_e32 v0, 32, v0
	v_lshl_add_u64 v[66:67], v[148:149], 0, s[22:23]
	s_mov_b64 s[22:23], 0x48000
	v_ldexp_f32 v0, v68, v0
	v_fmamk_f32 v0, v0, 0x30800000, v240
	v_rsq_f32_e32 v0, v0
	v_add_co_u32_e32 v68, vcc, s15, v148
	s_mov_b32 s15, 0x48000
	s_nop 0
	v_addc_co_u32_e32 v69, vcc, 0, v149, vcc
	v_pk_mul_f32 v[64:65], v[64:65], v[0:1] op_sel_hi:[1,0]
	v_pk_mul_f32 v[62:63], v[62:63], v[0:1] op_sel_hi:[1,0]
	v_pk_mul_f32 v[60:61], v[60:61], v[0:1] op_sel_hi:[1,0]
	v_pk_mul_f32 v[58:59], v[58:59], v[0:1] op_sel_hi:[1,0]
	v_pk_mul_f32 v[70:71], v[52:53], v[0:1] op_sel_hi:[1,0]
	v_pk_mul_f32 v[72:73], v[50:51], v[0:1] op_sel_hi:[1,0]
	v_cvt_pk_bf16_f32 v50, v62, v63
	v_cvt_pk_bf16_f32 v51, v64, v65
	v_cvt_pk_bf16_f32 v52, v58, v59
	v_cvt_pk_bf16_f32 v53, v60, v61
	v_pk_mul_f32 v[56:57], v[56:57], v[0:1] op_sel_hi:[1,0]
	v_pk_mul_f32 v[54:55], v[54:55], v[0:1] op_sel_hi:[1,0]
	global_store_dwordx4 v[68:69], v[50:53], off
	s_nop 1
	v_cvt_pk_bf16_f32 v50, v54, v55
	v_cvt_pk_bf16_f32 v51, v56, v57
	v_cvt_pk_bf16_f32 v52, v72, v73
	v_cvt_pk_bf16_f32 v53, v70, v71
	global_store_dwordx4 v[66:67], v[50:53], off offset:256
	v_ffbh_u32_e32 v0, v201
	v_min_u32_e32 v0, 32, v0
	v_lshlrev_b64 v[50:51], v0, v[200:201]
	v_min_u32_e32 v50, 1, v50
	v_or_b32_e32 v50, v51, v50
	v_cvt_f32_u32_e32 v52, v50
	v_sub_u32_e32 v0, 32, v0
	v_lshl_add_u64 v[50:51], v[148:149], 0, s[22:23]
	s_mov_b64 s[22:23], 0x50000
	v_ldexp_f32 v0, v52, v0
	v_fmamk_f32 v0, v0, 0x30800000, v240
	v_rsq_f32_e32 v0, v0
	v_add_co_u32_e32 v52, vcc, s15, v148
	s_mov_b32 s15, 0x50000
	s_nop 0
	v_addc_co_u32_e32 v53, vcc, 0, v149, vcc
	v_pk_mul_f32 v[48:49], v[48:49], v[0:1] op_sel_hi:[1,0]
	v_pk_mul_f32 v[46:47], v[46:47], v[0:1] op_sel_hi:[1,0]
	v_pk_mul_f32 v[44:45], v[44:45], v[0:1] op_sel_hi:[1,0]
	v_pk_mul_f32 v[42:43], v[42:43], v[0:1] op_sel_hi:[1,0]
	v_pk_mul_f32 v[54:55], v[36:37], v[0:1] op_sel_hi:[1,0]
	v_pk_mul_f32 v[56:57], v[34:35], v[0:1] op_sel_hi:[1,0]
	v_cvt_pk_bf16_f32 v34, v46, v47
	v_cvt_pk_bf16_f32 v35, v48, v49
	v_cvt_pk_bf16_f32 v36, v42, v43
	v_cvt_pk_bf16_f32 v37, v44, v45
	v_pk_mul_f32 v[40:41], v[40:41], v[0:1] op_sel_hi:[1,0]
	v_pk_mul_f32 v[38:39], v[38:39], v[0:1] op_sel_hi:[1,0]
	global_store_dwordx4 v[52:53], v[34:37], off
	s_nop 1
	v_cvt_pk_bf16_f32 v34, v38, v39
	v_cvt_pk_bf16_f32 v35, v40, v41
	v_cvt_pk_bf16_f32 v36, v56, v57
	v_cvt_pk_bf16_f32 v37, v54, v55
	global_store_dwordx4 v[50:51], v[34:37], off offset:256
	v_ffbh_u32_e32 v0, v203
	v_min_u32_e32 v0, 32, v0
	v_lshlrev_b64 v[34:35], v0, v[202:203]
	v_min_u32_e32 v34, 1, v34
	v_or_b32_e32 v34, v35, v34
	v_cvt_f32_u32_e32 v36, v34
	v_sub_u32_e32 v0, 32, v0
	v_lshl_add_u64 v[34:35], v[148:149], 0, s[22:23]
	s_mov_b64 s[22:23], 0x58000
	v_ldexp_f32 v0, v36, v0
	v_fmamk_f32 v0, v0, 0x30800000, v240
	v_rsq_f32_e32 v0, v0
	v_add_co_u32_e32 v36, vcc, s15, v148
	s_mov_b32 s15, 0x58000
	s_nop 0
	v_addc_co_u32_e32 v37, vcc, 0, v149, vcc
	v_pk_mul_f32 v[32:33], v[32:33], v[0:1] op_sel_hi:[1,0]
	v_pk_mul_f32 v[30:31], v[30:31], v[0:1] op_sel_hi:[1,0]
	v_pk_mul_f32 v[28:29], v[28:29], v[0:1] op_sel_hi:[1,0]
	v_pk_mul_f32 v[26:27], v[26:27], v[0:1] op_sel_hi:[1,0]
	v_pk_mul_f32 v[38:39], v[20:21], v[0:1] op_sel_hi:[1,0]
	v_pk_mul_f32 v[40:41], v[18:19], v[0:1] op_sel_hi:[1,0]
	v_cvt_pk_bf16_f32 v18, v30, v31
	v_cvt_pk_bf16_f32 v19, v32, v33
	v_cvt_pk_bf16_f32 v20, v26, v27
	v_cvt_pk_bf16_f32 v21, v28, v29
	v_pk_mul_f32 v[24:25], v[24:25], v[0:1] op_sel_hi:[1,0]
	v_pk_mul_f32 v[22:23], v[22:23], v[0:1] op_sel_hi:[1,0]
	global_store_dwordx4 v[36:37], v[18:21], off
	s_nop 1
	v_cvt_pk_bf16_f32 v18, v22, v23
	v_cvt_pk_bf16_f32 v19, v24, v25
	v_cvt_pk_bf16_f32 v20, v40, v41
	v_cvt_pk_bf16_f32 v21, v38, v39
	global_store_dwordx4 v[34:35], v[18:21], off offset:256
	v_ffbh_u32_e32 v0, v205
	v_min_u32_e32 v0, 32, v0
	v_lshlrev_b64 v[18:19], v0, v[204:205]
	v_min_u32_e32 v18, 1, v18
	v_or_b32_e32 v18, v19, v18
	v_cvt_f32_u32_e32 v20, v18
	v_sub_u32_e32 v0, 32, v0
	v_lshl_add_u64 v[18:19], v[148:149], 0, s[22:23]
	v_ldexp_f32 v0, v20, v0
	v_fmamk_f32 v0, v0, 0x30800000, v240
	v_rsq_f32_e32 v0, v0
	v_add_co_u32_e32 v20, vcc, s15, v148
	v_pk_mul_f32 v[16:17], v[16:17], v[0:1] op_sel_hi:[1,0]
	s_nop 0
	v_addc_co_u32_e32 v21, vcc, 0, v149, vcc
	v_pk_mul_f32 v[14:15], v[14:15], v[0:1] op_sel_hi:[1,0]
	v_pk_mul_f32 v[12:13], v[12:13], v[0:1] op_sel_hi:[1,0]
	v_pk_mul_f32 v[10:11], v[10:11], v[0:1] op_sel_hi:[1,0]
	v_pk_mul_f32 v[22:23], v[4:5], v[0:1] op_sel_hi:[1,0]
	v_pk_mul_f32 v[24:25], v[2:3], v[0:1] op_sel_hi:[1,0]
	v_cvt_pk_bf16_f32 v2, v14, v15
	v_cvt_pk_bf16_f32 v3, v16, v17
	v_cvt_pk_bf16_f32 v4, v10, v11
	v_cvt_pk_bf16_f32 v5, v12, v13
	v_pk_mul_f32 v[8:9], v[8:9], v[0:1] op_sel_hi:[1,0]
	v_pk_mul_f32 v[6:7], v[6:7], v[0:1] op_sel_hi:[1,0]
	global_store_dwordx4 v[20:21], v[2:5], off
	s_nop 1
	v_cvt_pk_bf16_f32 v2, v6, v7
	v_cvt_pk_bf16_f32 v3, v8, v9
	v_cvt_pk_bf16_f32 v4, v24, v25
	v_cvt_pk_bf16_f32 v5, v22, v23
	global_store_dwordx4 v[18:19], v[2:5], off offset:256
	s_andn2_b64 vcc, exec, s[6:7]
	s_mov_b64 s[6:7], -1
	s_cbranch_vccnz .LBB0_130
